# short-base stagger: common transposer stagger sleep reduced from 4 to 1 units (per-loader offsets 1,6,11,16)
# baseline (speedup 1.0000x reference)
; #define LAS __attribute__((address_space(3)))
; #define GAS __attribute__((address_space(1)))
; #define LDS_WAIT() asm volatile("s_waitcnt lgkmcnt(0)" ::: "memory")
; __device__ __forceinline__ void p0_transpose_item(const GAS float* W, int K, int N, GAS bf16* WT, int mode, LAS float* scr, int item, int lane) {
;     const int nblk = N / 32, kb = item / nblk, nb = item % nblk, k0 = 64 * kb, n0 = 32 * nb;
;     int r0 = n0;
;     if (mode & 1) { r0 = (n0 < DFF) ? (n0 / 128) * 256 + (n0 % 128) : ((n0 - DFF) / 128) * 256 + 128 + ((n0 - DFF) % 128); }
;     float tv[32];
; #pragma unroll
;     for (int i = 0; i < 32; ++i) tv[i] = __builtin_nontemporal_load(&W[(size_t)(k0 + 2 * i + (lane >> 5)) * N + n0 + (lane & 31)]);
; #pragma unroll
;     for (int i = 0; i < 32; ++i) scr[(2 * i + (lane >> 5)) * 33 + (lane & 31)] = tv[i];
;     LDS_WAIT();
.Lxp_go0:
	s_sleep 1
	s_cmp_eq_u32 s1, 0
	s_cbranch_scc1 .Lxp_sl0
	s_sleep 5
	s_cmp_eq_u32 s1, 1
	s_cbranch_scc1 .Lxp_sl0
	s_sleep 5
	s_cmp_eq_u32 s1, 2
	s_cbranch_scc1 .Lxp_sl0
	s_sleep 5
